# gemm_mid KV up-projection tiles hand-written (3-stage A ring, direct weight fragments, swapped MFMA operands, direct stores, next-tile prefetch); Q/conv tiles stay compiled
# baseline (speedup 1.0000x reference)
.Lgm_entry:
	v_readlane_b32 s0, v254, 41
	v_readlane_b32 s4, v253, 0
	v_readlane_b32 s5, v255, 23
	s_mov_b32 s7, 0
	s_movk_i32 s6, 408
	s_cmp_eq_u32 s0, 0
	s_cbranch_scc1 .Lgm_g1
	v_readlane_b32 s7, v254, 43
	s_mul_i32 s7, s7, 17
	v_readlane_b32 s4, v254, 44
	v_readlane_b32 s5, v254, 45
	s_movk_i32 s6, 51
.Lgm_g1:
	v_and_b32_e32 v138, 31, v143
	v_bfe_u32 v139, v143, 5, 1
	v_mul_u32_u24_e32 v130, 144, v138
	v_lshl_add_u32 v130, v139, 4, v130
	v_lshrrev_b32_e32 v141, 3, v143
	v_and_b32_e32 v128, 7, v143
	v_mul_u32_u24_e32 v131, 144, v141
	v_lshl_add_u32 v131, v128, 4, v131
	v_readfirstlane_b32 s96, v143
	s_lshr_b32 s96, s96, 6
	s_lshl_b32 s96, s96, 5
	s_sub_i32 s4, s4, s5
	s_mov_b32 s100, 0
.Lgm_fe_top:
	s_mov_b32 s101, 0
	s_add_i32 s4, s4, s5
	s_cmp_ge_i32 s4, s6
	s_cbranch_scc1 .Lgm_fe_end
	s_mul_hi_u32 s0, s4, 0xaaaaaaab
	s_lshr_b32 s0, s0, 1
	s_mul_i32 s1, s0, 3
	s_sub_i32 s1, s4, s1
	s_add_i32 s0, s0, s7
	s_lshl_b32 s80, s0, 8
	s_cmp_eq_u32 s1, 0
	s_cbranch_scc1 .Lgm_fe_k0
	s_cmp_eq_u32 s1, 1
	s_cbranch_scc1 .Lgm_fe_k1
	s_cmp_eq_u32 s1, 2
	s_cbranch_scc1 .Lgm_fe_k2
	s_branch .Lgm_done
.Lgm_fe_k0:
	s_mov_b32 s101, 1
	s_mov_b32 s26, 0
	s_mov_b32 s79, 1
	s_mov_b32 s81, 1
	s_mul_i32 s32, s80, 5184
	s_add_u32 s32, s32, 97243648
	s_add_u32 s10, s50, s32
	s_addc_u32 s11, s51, 0
	s_mul_i32 s32, s74, 196608
	s_add_u32 s32, s32, 12189696
	s_add_u32 s12, s50, s32
	s_addc_u32 s13, s51, 0
	v_lshrrev_b32_e32 v141, 3, v143
	v_and_b32_e32 v128, 7, v143
	v_mul_u32_u24_e32 v132, 5184, v141
	v_lshl_add_u32 v132, v128, 4, v132
	v_add_u32_e32 v133, 331776, v132
	v_add_u32_e32 v134, 663552, v132
	v_add_u32_e32 v135, 995328, v132
	v_and_b32_e32 v138, 31, v143
	v_bfe_u32 v139, v143, 5, 1
	v_lshrrev_b32_e32 v140, 6, v143
	v_lshl_add_u32 v136, v140, 5, v138
	v_lshlrev_b32_e32 v136, 8, v136
	v_lshl_add_u32 v136, v139, 4, v136
	s_branch .Lgm_fe_end
.Lgm_fe_k1:
	s_mov_b32 s101, 1
	s_mov_b32 s26, 256
	s_mov_b32 s79, 1
	s_mov_b32 s81, 1
	s_mul_i32 s32, s80, 5184
	s_add_u32 s32, s32, 97243648
	s_add_u32 s10, s50, s32
	s_addc_u32 s11, s51, 0
	s_mul_i32 s32, s74, 196608
	s_add_u32 s32, s32, 12255232
	s_add_u32 s12, s50, s32
	s_addc_u32 s13, s51, 0
	v_lshrrev_b32_e32 v141, 3, v143
	v_and_b32_e32 v128, 7, v143
	v_mul_u32_u24_e32 v132, 5184, v141
	v_lshl_add_u32 v132, v128, 4, v132
	v_add_u32_e32 v133, 331776, v132
	v_add_u32_e32 v134, 663552, v132
	v_add_u32_e32 v135, 995328, v132
	v_and_b32_e32 v138, 31, v143
	v_bfe_u32 v139, v143, 5, 1
	v_lshrrev_b32_e32 v140, 6, v143
	v_lshl_add_u32 v136, v140, 5, v138
	v_lshlrev_b32_e32 v136, 8, v136
	v_lshl_add_u32 v136, v139, 4, v136
	s_branch .Lgm_fe_end
.Lgm_fe_k2:
	s_mov_b32 s101, 1
	s_mov_b32 s26, 512
	s_mov_b32 s79, 1
	s_mov_b32 s81, 1
	s_mul_i32 s32, s80, 5184
	s_add_u32 s32, s32, 97243648
	s_add_u32 s10, s50, s32
	s_addc_u32 s11, s51, 0
	s_mul_i32 s32, s74, 196608
	s_add_u32 s32, s32, 12320768
	s_add_u32 s12, s50, s32
	s_addc_u32 s13, s51, 0
	v_lshrrev_b32_e32 v141, 3, v143
	v_and_b32_e32 v128, 7, v143
	v_mul_u32_u24_e32 v132, 5184, v141
	v_lshl_add_u32 v132, v128, 4, v132
	v_add_u32_e32 v133, 331776, v132
	v_add_u32_e32 v134, 663552, v132
	v_add_u32_e32 v135, 995328, v132
	v_and_b32_e32 v138, 31, v143
	v_bfe_u32 v139, v143, 5, 1
	v_lshrrev_b32_e32 v140, 6, v143
	v_lshl_add_u32 v136, v140, 5, v138
	v_lshlrev_b32_e32 v136, 8, v136
	v_lshl_add_u32 v136, v139, 4, v136
	s_branch .Lgm_fe_end
.Lgm_fe_end:
	s_cmp_eq_u32 s101, 0
	s_cbranch_scc1 .Lgm_done
	global_load_dwordx4 v[216:219], v132, s[10:11]
	global_load_dwordx4 v[220:223], v133, s[10:11]
	global_load_dwordx4 v[224:227], v134, s[10:11]
	global_load_dwordx4 v[228:231], v135, s[10:11]
	global_load_dwordx4 v[144:147], v132, s[10:11] offset:128
	global_load_dwordx4 v[148:151], v133, s[10:11] offset:128
	global_load_dwordx4 v[152:155], v134, s[10:11] offset:128
	global_load_dwordx4 v[156:159], v135, s[10:11] offset:128
	global_load_dwordx4 v[184:187], v136, s[12:13] offset:0
	global_load_dwordx4 v[188:191], v136, s[12:13] offset:32
	global_load_dwordx4 v[192:195], v136, s[12:13] offset:64
	global_load_dwordx4 v[196:199], v136, s[12:13] offset:96
	s_add_u32 s10, s10, 256
	s_addc_u32 s11, s11, 0
	s_add_u32 s12, s12, 128
	s_addc_u32 s13, s13, 0
.Lgm_tile:
	s_mov_b32 s30, s79
	s_mov_b32 s31, s80
	s_mov_b32 s27, s26
	s_mov_b32 s19, s81
	s_lshl_b32 s56, s81, 1
	s_sub_u32 s56, s56, 2
	s_mov_b32 s16, 0
	s_mov_b32 s17, 36864
	s_mov_b32 s18, 73728
	v_mov_b32_e32 v0, 0
	v_mov_b32_e32 v1, 0
	v_mov_b32_e32 v2, 0
	v_mov_b32_e32 v3, 0
	v_mov_b32_e32 v4, 0
	v_mov_b32_e32 v5, 0
	v_mov_b32_e32 v6, 0
	v_mov_b32_e32 v7, 0
	v_mov_b32_e32 v8, 0
	v_mov_b32_e32 v9, 0
	v_mov_b32_e32 v10, 0
	v_mov_b32_e32 v11, 0
	v_mov_b32_e32 v12, 0
	v_mov_b32_e32 v13, 0
	v_mov_b32_e32 v14, 0
	v_mov_b32_e32 v15, 0
	v_mov_b32_e32 v16, 0
	v_mov_b32_e32 v17, 0
	v_mov_b32_e32 v18, 0
	v_mov_b32_e32 v19, 0
	v_mov_b32_e32 v20, 0
	v_mov_b32_e32 v21, 0
	v_mov_b32_e32 v22, 0
	v_mov_b32_e32 v23, 0
	v_mov_b32_e32 v24, 0
	v_mov_b32_e32 v25, 0
	v_mov_b32_e32 v26, 0
	v_mov_b32_e32 v27, 0
	v_mov_b32_e32 v28, 0
	v_mov_b32_e32 v29, 0
	v_mov_b32_e32 v30, 0
	v_mov_b32_e32 v31, 0
	v_mov_b32_e32 v32, 0
	v_mov_b32_e32 v33, 0
	v_mov_b32_e32 v34, 0
	v_mov_b32_e32 v35, 0
	v_mov_b32_e32 v36, 0
	v_mov_b32_e32 v37, 0
	v_mov_b32_e32 v38, 0
	v_mov_b32_e32 v39, 0
	v_mov_b32_e32 v40, 0
	v_mov_b32_e32 v41, 0
	v_mov_b32_e32 v42, 0
	v_mov_b32_e32 v43, 0
	v_mov_b32_e32 v44, 0
	v_mov_b32_e32 v45, 0
	v_mov_b32_e32 v46, 0
	v_mov_b32_e32 v47, 0
	v_mov_b32_e32 v48, 0
	v_mov_b32_e32 v49, 0
	v_mov_b32_e32 v50, 0
	v_mov_b32_e32 v51, 0
	v_mov_b32_e32 v52, 0
	v_mov_b32_e32 v53, 0
	v_mov_b32_e32 v54, 0
	v_mov_b32_e32 v55, 0
	v_mov_b32_e32 v56, 0
	v_mov_b32_e32 v57, 0
	v_mov_b32_e32 v58, 0
	v_mov_b32_e32 v59, 0
	v_mov_b32_e32 v60, 0
	v_mov_b32_e32 v61, 0
	v_mov_b32_e32 v62, 0
	v_mov_b32_e32 v63, 0
	v_mov_b32_e32 v64, 0
	v_mov_b32_e32 v65, 0
	v_mov_b32_e32 v66, 0
	v_mov_b32_e32 v67, 0
	v_mov_b32_e32 v68, 0
	v_mov_b32_e32 v69, 0
	v_mov_b32_e32 v70, 0
	v_mov_b32_e32 v71, 0
	v_mov_b32_e32 v72, 0
	v_mov_b32_e32 v73, 0
	v_mov_b32_e32 v74, 0
	v_mov_b32_e32 v75, 0
	v_mov_b32_e32 v76, 0
	v_mov_b32_e32 v77, 0
	v_mov_b32_e32 v78, 0
	v_mov_b32_e32 v79, 0
	v_mov_b32_e32 v80, 0
	v_mov_b32_e32 v81, 0
	v_mov_b32_e32 v82, 0
	v_mov_b32_e32 v83, 0
	v_mov_b32_e32 v84, 0
	v_mov_b32_e32 v85, 0
	v_mov_b32_e32 v86, 0
	v_mov_b32_e32 v87, 0
	v_mov_b32_e32 v88, 0
	v_mov_b32_e32 v89, 0
	v_mov_b32_e32 v90, 0
	v_mov_b32_e32 v91, 0
	v_mov_b32_e32 v92, 0
	v_mov_b32_e32 v93, 0
	v_mov_b32_e32 v94, 0
	v_mov_b32_e32 v95, 0
	v_mov_b32_e32 v96, 0
	v_mov_b32_e32 v97, 0
	v_mov_b32_e32 v98, 0
	v_mov_b32_e32 v99, 0
	v_mov_b32_e32 v100, 0
	v_mov_b32_e32 v101, 0
	v_mov_b32_e32 v102, 0
	v_mov_b32_e32 v103, 0
	v_mov_b32_e32 v104, 0
	v_mov_b32_e32 v105, 0
	v_mov_b32_e32 v106, 0
	v_mov_b32_e32 v107, 0
	v_mov_b32_e32 v108, 0
	v_mov_b32_e32 v109, 0
	v_mov_b32_e32 v110, 0
	v_mov_b32_e32 v111, 0
	v_mov_b32_e32 v112, 0
	v_mov_b32_e32 v113, 0
	v_mov_b32_e32 v114, 0
	v_mov_b32_e32 v115, 0
	v_mov_b32_e32 v116, 0
	v_mov_b32_e32 v117, 0
	v_mov_b32_e32 v118, 0
	v_mov_b32_e32 v119, 0
	v_mov_b32_e32 v120, 0
	v_mov_b32_e32 v121, 0
	v_mov_b32_e32 v122, 0
	v_mov_b32_e32 v123, 0
	v_mov_b32_e32 v124, 0
	v_mov_b32_e32 v125, 0
	v_mov_b32_e32 v126, 0
	v_mov_b32_e32 v127, 0
	s_cmp_eq_u32 s100, 32
	s_cbranch_scc1 .Lgm_w_32
	s_cmp_eq_u32 s100, 56
	s_cbranch_scc1 .Lgm_w_56
	s_waitcnt vmcnt(4)
	s_branch .Lgm_w_j
.Lgm_w_32:
	s_waitcnt vmcnt(36)
	s_branch .Lgm_w_j
.Lgm_w_56:
	s_waitcnt vmcnt(60)
	s_branch .Lgm_w_j
.Lgm_w_j:
	ds_write_b128 v131, v[216:219] offset:0
	ds_write_b128 v131, v[220:223] offset:9216
	ds_write_b128 v131, v[224:227] offset:18432
	ds_write_b128 v131, v[228:231] offset:27648
	ds_write_b128 v131, v[144:147] offset:36864
	ds_write_b128 v131, v[148:151] offset:46080
	ds_write_b128 v131, v[152:155] offset:55296
	ds_write_b128 v131, v[156:159] offset:64512
	global_load_dwordx4 v[216:219], v132, s[10:11]
	global_load_dwordx4 v[220:223], v133, s[10:11]
	global_load_dwordx4 v[224:227], v134, s[10:11]
	global_load_dwordx4 v[228:231], v135, s[10:11]
	s_add_u32 s10, s10, 128
	s_addc_u32 s11, s11, 0
	v_add_u32_e32 v176, s16, v130
	s_waitcnt lgkmcnt(0)
	s_barrier
	ds_read_b128 v[144:147], v176 offset:0
	ds_read_b128 v[148:151], v176 offset:4608
	ds_read_b128 v[152:155], v176 offset:9216
	ds_read_b128 v[156:159], v176 offset:13824
	ds_read_b128 v[160:163], v176 offset:18432
	ds_read_b128 v[164:167], v176 offset:23040
.Lgm_kloop:
	v_add_u32_e32 v177, s17, v130
	s_waitcnt vmcnt(4)
	s_waitcnt lgkmcnt(5)
	v_mfma_f32_32x32x16_bf16 v[0:15], v[184:187], v[144:147], v[0:15]
	ds_read_b128 v[168:171], v176 offset:27648
	s_waitcnt lgkmcnt(5)
	v_mfma_f32_32x32x16_bf16 v[16:31], v[184:187], v[148:151], v[16:31]
	ds_read_b128 v[172:175], v176 offset:32256
	global_load_dwordx4 v[200:203], v136, s[12:13] offset:0
	s_waitcnt lgkmcnt(5)
	v_mfma_f32_32x32x16_bf16 v[32:47], v[184:187], v[152:155], v[32:47]
	ds_read_b128 v[144:147], v176 offset:32
	s_waitcnt lgkmcnt(5)
	v_mfma_f32_32x32x16_bf16 v[48:63], v[184:187], v[156:159], v[48:63]
	ds_read_b128 v[148:151], v176 offset:4640
	global_load_dwordx4 v[204:207], v136, s[12:13] offset:32
	s_waitcnt lgkmcnt(5)
	v_mfma_f32_32x32x16_bf16 v[64:79], v[184:187], v[160:163], v[64:79]
	ds_read_b128 v[152:155], v176 offset:9248
	s_waitcnt lgkmcnt(5)
	v_mfma_f32_32x32x16_bf16 v[80:95], v[184:187], v[164:167], v[80:95]
	ds_read_b128 v[156:159], v176 offset:13856
	global_load_dwordx4 v[208:211], v136, s[12:13] offset:64
	s_waitcnt lgkmcnt(5)
	v_mfma_f32_32x32x16_bf16 v[96:111], v[184:187], v[168:171], v[96:111]
	ds_read_b128 v[160:163], v176 offset:18464
	s_waitcnt lgkmcnt(5)
	v_mfma_f32_32x32x16_bf16 v[112:127], v[184:187], v[172:175], v[112:127]
	ds_read_b128 v[164:167], v176 offset:23072
	global_load_dwordx4 v[212:215], v136, s[12:13] offset:96
	s_waitcnt lgkmcnt(5)
	v_mfma_f32_32x32x16_bf16 v[0:15], v[188:191], v[144:147], v[0:15]
	ds_read_b128 v[168:171], v176 offset:27680
	s_waitcnt lgkmcnt(5)
	v_mfma_f32_32x32x16_bf16 v[16:31], v[188:191], v[148:151], v[16:31]
	ds_read_b128 v[172:175], v176 offset:32288
	s_cmp_eq_u32 s56, 0
	s_cbranch_scc1 .Lgm_sk_0_0
	s_waitcnt vmcnt(7)
.Lgm_sk_0_0:
	v_add_u32_e32 v179, s18, v131
	ds_write_b128 v179, v[216:219] offset:0
	global_load_dwordx4 v[216:219], v132, s[10:11]
	s_waitcnt lgkmcnt(6)
	v_mfma_f32_32x32x16_bf16 v[32:47], v[188:191], v[152:155], v[32:47]
	ds_read_b128 v[144:147], v176 offset:64
	s_waitcnt lgkmcnt(6)
	v_mfma_f32_32x32x16_bf16 v[48:63], v[188:191], v[156:159], v[48:63]
	ds_read_b128 v[148:151], v176 offset:4672
	s_cmp_eq_u32 s56, 0
	s_cbranch_scc1 .Lgm_sk_0_1
	s_waitcnt vmcnt(7)
.Lgm_sk_0_1:
	v_add_u32_e32 v179, s18, v131
	ds_write_b128 v179, v[220:223] offset:9216
	global_load_dwordx4 v[220:223], v133, s[10:11]
	s_waitcnt lgkmcnt(7)
	v_mfma_f32_32x32x16_bf16 v[64:79], v[188:191], v[160:163], v[64:79]
	ds_read_b128 v[152:155], v176 offset:9280
	s_waitcnt lgkmcnt(7)
	v_mfma_f32_32x32x16_bf16 v[80:95], v[188:191], v[164:167], v[80:95]
	ds_read_b128 v[156:159], v176 offset:13888
	s_cmp_eq_u32 s56, 0
	s_cbranch_scc1 .Lgm_sk_0_2
	s_waitcnt vmcnt(7)
.Lgm_sk_0_2:
	v_add_u32_e32 v179, s18, v131
	ds_write_b128 v179, v[224:227] offset:18432
	global_load_dwordx4 v[224:227], v134, s[10:11]
	s_waitcnt lgkmcnt(8)
	v_mfma_f32_32x32x16_bf16 v[96:111], v[188:191], v[168:171], v[96:111]
	ds_read_b128 v[160:163], v176 offset:18496
	s_waitcnt lgkmcnt(8)
	v_mfma_f32_32x32x16_bf16 v[112:127], v[188:191], v[172:175], v[112:127]
	ds_read_b128 v[164:167], v176 offset:23104
	s_cmp_eq_u32 s56, 0
	s_cbranch_scc1 .Lgm_sk_0_3
	s_waitcnt vmcnt(7)
.Lgm_sk_0_3:
	v_add_u32_e32 v179, s18, v131
	ds_write_b128 v179, v[228:231] offset:27648
	global_load_dwordx4 v[228:231], v135, s[10:11]
	s_waitcnt lgkmcnt(8)
	v_mfma_f32_32x32x16_bf16 v[0:15], v[192:195], v[144:147], v[0:15]
	ds_read_b128 v[168:171], v176 offset:27712
	s_add_u32 s10, s10, 128
	s_addc_u32 s11, s11, 0
	s_add_u32 s12, s12, 128
	s_addc_u32 s13, s13, 0
	s_waitcnt lgkmcnt(8)
	v_mfma_f32_32x32x16_bf16 v[16:31], v[192:195], v[148:151], v[16:31]
	ds_read_b128 v[172:175], v176 offset:32320
	s_waitcnt lgkmcnt(7)
	v_mfma_f32_32x32x16_bf16 v[32:47], v[192:195], v[152:155], v[32:47]
	ds_read_b128 v[144:147], v176 offset:96
	s_waitcnt lgkmcnt(7)
	v_mfma_f32_32x32x16_bf16 v[48:63], v[192:195], v[156:159], v[48:63]
	ds_read_b128 v[148:151], v176 offset:4704
	s_waitcnt lgkmcnt(6)
	v_mfma_f32_32x32x16_bf16 v[64:79], v[192:195], v[160:163], v[64:79]
	ds_read_b128 v[152:155], v176 offset:9312
	s_waitcnt lgkmcnt(6)
	v_mfma_f32_32x32x16_bf16 v[80:95], v[192:195], v[164:167], v[80:95]
	ds_read_b128 v[156:159], v176 offset:13920
	s_waitcnt lgkmcnt(5)
	v_mfma_f32_32x32x16_bf16 v[96:111], v[192:195], v[168:171], v[96:111]
	ds_read_b128 v[160:163], v176 offset:18528
	s_waitcnt lgkmcnt(5)
	v_mfma_f32_32x32x16_bf16 v[112:127], v[192:195], v[172:175], v[112:127]
	ds_read_b128 v[164:167], v176 offset:23136
	s_waitcnt lgkmcnt(5)
	v_mfma_f32_32x32x16_bf16 v[0:15], v[196:199], v[144:147], v[0:15]
	ds_read_b128 v[168:171], v176 offset:27744
	s_waitcnt lgkmcnt(5)
	v_mfma_f32_32x32x16_bf16 v[16:31], v[196:199], v[148:151], v[16:31]
	ds_read_b128 v[172:175], v176 offset:32352
	s_waitcnt lgkmcnt(5)
	v_mfma_f32_32x32x16_bf16 v[32:47], v[196:199], v[152:155], v[32:47]
	ds_read_b128 v[144:147], v177 offset:0
	s_waitcnt lgkmcnt(5)
	v_mfma_f32_32x32x16_bf16 v[48:63], v[196:199], v[156:159], v[48:63]
	ds_read_b128 v[148:151], v177 offset:4608
	s_waitcnt lgkmcnt(5)
	v_mfma_f32_32x32x16_bf16 v[64:79], v[196:199], v[160:163], v[64:79]
	ds_read_b128 v[152:155], v177 offset:9216
	s_waitcnt lgkmcnt(5)
	v_mfma_f32_32x32x16_bf16 v[80:95], v[196:199], v[164:167], v[80:95]
	ds_read_b128 v[156:159], v177 offset:13824
	s_waitcnt lgkmcnt(5)
	v_mfma_f32_32x32x16_bf16 v[96:111], v[196:199], v[168:171], v[96:111]
	ds_read_b128 v[160:163], v177 offset:18432
	s_waitcnt lgkmcnt(5)
	v_mfma_f32_32x32x16_bf16 v[112:127], v[196:199], v[172:175], v[112:127]
	ds_read_b128 v[164:167], v177 offset:23040
	s_mov_b32 s0, s16
	s_mov_b32 s16, s17
	s_mov_b32 s17, s18
	s_mov_b32 s18, s0
	v_mov_b32_e32 v176, v177
	s_cmp_lg_u32 s56, 0
	s_cselect_b32 s0, 1, 0
	s_sub_u32 s56, s56, s0
	s_barrier
	v_add_u32_e32 v177, s17, v130
	s_waitcnt vmcnt(4)
	s_waitcnt lgkmcnt(5)
	v_mfma_f32_32x32x16_bf16 v[0:15], v[200:203], v[144:147], v[0:15]
	ds_read_b128 v[168:171], v176 offset:27648
	s_waitcnt lgkmcnt(5)
	v_mfma_f32_32x32x16_bf16 v[16:31], v[200:203], v[148:151], v[16:31]
	ds_read_b128 v[172:175], v176 offset:32256
	global_load_dwordx4 v[184:187], v136, s[12:13] offset:0
	s_waitcnt lgkmcnt(5)
	v_mfma_f32_32x32x16_bf16 v[32:47], v[200:203], v[152:155], v[32:47]
	ds_read_b128 v[144:147], v176 offset:32
	s_waitcnt lgkmcnt(5)
	v_mfma_f32_32x32x16_bf16 v[48:63], v[200:203], v[156:159], v[48:63]
	ds_read_b128 v[148:151], v176 offset:4640
	global_load_dwordx4 v[188:191], v136, s[12:13] offset:32
	s_waitcnt lgkmcnt(5)
	v_mfma_f32_32x32x16_bf16 v[64:79], v[200:203], v[160:163], v[64:79]
	ds_read_b128 v[152:155], v176 offset:9248
	s_waitcnt lgkmcnt(5)
	v_mfma_f32_32x32x16_bf16 v[80:95], v[200:203], v[164:167], v[80:95]
	ds_read_b128 v[156:159], v176 offset:13856
	global_load_dwordx4 v[192:195], v136, s[12:13] offset:64
	s_waitcnt lgkmcnt(5)
	v_mfma_f32_32x32x16_bf16 v[96:111], v[200:203], v[168:171], v[96:111]
	ds_read_b128 v[160:163], v176 offset:18464
	s_waitcnt lgkmcnt(5)
	v_mfma_f32_32x32x16_bf16 v[112:127], v[200:203], v[172:175], v[112:127]
	ds_read_b128 v[164:167], v176 offset:23072
	global_load_dwordx4 v[196:199], v136, s[12:13] offset:96
	s_waitcnt lgkmcnt(5)
	v_mfma_f32_32x32x16_bf16 v[0:15], v[204:207], v[144:147], v[0:15]
	ds_read_b128 v[168:171], v176 offset:27680
	s_waitcnt lgkmcnt(5)
	v_mfma_f32_32x32x16_bf16 v[16:31], v[204:207], v[148:151], v[16:31]
	ds_read_b128 v[172:175], v176 offset:32288
	s_cmp_eq_u32 s56, 0
	s_cbranch_scc1 .Lgm_sk_1_0
	s_waitcnt vmcnt(7)
.Lgm_sk_1_0:
	v_add_u32_e32 v179, s18, v131
	ds_write_b128 v179, v[216:219] offset:0
	global_load_dwordx4 v[216:219], v132, s[10:11]
	s_waitcnt lgkmcnt(6)
	v_mfma_f32_32x32x16_bf16 v[32:47], v[204:207], v[152:155], v[32:47]
	ds_read_b128 v[144:147], v176 offset:64
	s_waitcnt lgkmcnt(6)
	v_mfma_f32_32x32x16_bf16 v[48:63], v[204:207], v[156:159], v[48:63]
	ds_read_b128 v[148:151], v176 offset:4672
	s_cmp_eq_u32 s56, 0
	s_cbranch_scc1 .Lgm_sk_1_1
	s_waitcnt vmcnt(7)
.Lgm_sk_1_1:
	v_add_u32_e32 v179, s18, v131
	ds_write_b128 v179, v[220:223] offset:9216
	global_load_dwordx4 v[220:223], v133, s[10:11]
	s_waitcnt lgkmcnt(7)
	v_mfma_f32_32x32x16_bf16 v[64:79], v[204:207], v[160:163], v[64:79]
	ds_read_b128 v[152:155], v176 offset:9280
	s_waitcnt lgkmcnt(7)
	v_mfma_f32_32x32x16_bf16 v[80:95], v[204:207], v[164:167], v[80:95]
	ds_read_b128 v[156:159], v176 offset:13888
	s_cmp_eq_u32 s56, 0
	s_cbranch_scc1 .Lgm_sk_1_2
	s_waitcnt vmcnt(7)
.Lgm_sk_1_2:
	v_add_u32_e32 v179, s18, v131
	ds_write_b128 v179, v[224:227] offset:18432
	global_load_dwordx4 v[224:227], v134, s[10:11]
	s_waitcnt lgkmcnt(8)
	v_mfma_f32_32x32x16_bf16 v[96:111], v[204:207], v[168:171], v[96:111]
	ds_read_b128 v[160:163], v176 offset:18496
	s_waitcnt lgkmcnt(8)
	v_mfma_f32_32x32x16_bf16 v[112:127], v[204:207], v[172:175], v[112:127]
	ds_read_b128 v[164:167], v176 offset:23104
	s_cmp_eq_u32 s56, 0
	s_cbranch_scc1 .Lgm_sk_1_3
	s_waitcnt vmcnt(7)
.Lgm_sk_1_3:
	v_add_u32_e32 v179, s18, v131
	ds_write_b128 v179, v[228:231] offset:27648
	global_load_dwordx4 v[228:231], v135, s[10:11]
	s_waitcnt lgkmcnt(8)
	v_mfma_f32_32x32x16_bf16 v[0:15], v[208:211], v[144:147], v[0:15]
	ds_read_b128 v[168:171], v176 offset:27712
	s_add_u32 s10, s10, 128
	s_addc_u32 s11, s11, 0
	s_add_u32 s12, s12, 128
	s_addc_u32 s13, s13, 0
	s_waitcnt lgkmcnt(8)
	v_mfma_f32_32x32x16_bf16 v[16:31], v[208:211], v[148:151], v[16:31]
	ds_read_b128 v[172:175], v176 offset:32320
	s_waitcnt lgkmcnt(7)
	v_mfma_f32_32x32x16_bf16 v[32:47], v[208:211], v[152:155], v[32:47]
	ds_read_b128 v[144:147], v176 offset:96
	s_waitcnt lgkmcnt(7)
	v_mfma_f32_32x32x16_bf16 v[48:63], v[208:211], v[156:159], v[48:63]
	ds_read_b128 v[148:151], v176 offset:4704
	s_waitcnt lgkmcnt(6)
	v_mfma_f32_32x32x16_bf16 v[64:79], v[208:211], v[160:163], v[64:79]
	ds_read_b128 v[152:155], v176 offset:9312
	s_waitcnt lgkmcnt(6)
	v_mfma_f32_32x32x16_bf16 v[80:95], v[208:211], v[164:167], v[80:95]
	ds_read_b128 v[156:159], v176 offset:13920
	s_waitcnt lgkmcnt(5)
	v_mfma_f32_32x32x16_bf16 v[96:111], v[208:211], v[168:171], v[96:111]
	ds_read_b128 v[160:163], v176 offset:18528
	s_waitcnt lgkmcnt(5)
	v_mfma_f32_32x32x16_bf16 v[112:127], v[208:211], v[172:175], v[112:127]
	ds_read_b128 v[164:167], v176 offset:23136
	s_waitcnt lgkmcnt(5)
	v_mfma_f32_32x32x16_bf16 v[0:15], v[212:215], v[144:147], v[0:15]
	ds_read_b128 v[168:171], v176 offset:27744
	s_waitcnt lgkmcnt(5)
	v_mfma_f32_32x32x16_bf16 v[16:31], v[212:215], v[148:151], v[16:31]
	ds_read_b128 v[172:175], v176 offset:32352
	s_waitcnt lgkmcnt(5)
	v_mfma_f32_32x32x16_bf16 v[32:47], v[212:215], v[152:155], v[32:47]
	ds_read_b128 v[144:147], v177 offset:0
	s_waitcnt lgkmcnt(5)
	v_mfma_f32_32x32x16_bf16 v[48:63], v[212:215], v[156:159], v[48:63]
	ds_read_b128 v[148:151], v177 offset:4608
	s_waitcnt lgkmcnt(5)
	v_mfma_f32_32x32x16_bf16 v[64:79], v[212:215], v[160:163], v[64:79]
	ds_read_b128 v[152:155], v177 offset:9216
	s_waitcnt lgkmcnt(5)
	v_mfma_f32_32x32x16_bf16 v[80:95], v[212:215], v[164:167], v[80:95]
	ds_read_b128 v[156:159], v177 offset:13824
	s_waitcnt lgkmcnt(5)
	v_mfma_f32_32x32x16_bf16 v[96:111], v[212:215], v[168:171], v[96:111]
	ds_read_b128 v[160:163], v177 offset:18432
	s_waitcnt lgkmcnt(5)
	v_mfma_f32_32x32x16_bf16 v[112:127], v[212:215], v[172:175], v[112:127]
	ds_read_b128 v[164:167], v177 offset:23040
	s_mov_b32 s0, s16
	s_mov_b32 s16, s17
	s_mov_b32 s17, s18
	s_mov_b32 s18, s0
	v_mov_b32_e32 v176, v177
	s_cmp_lg_u32 s56, 0
	s_cselect_b32 s0, 1, 0
	s_sub_u32 s56, s56, s0
	s_add_i32 s19, s19, -1
	s_barrier
	s_cmp_lg_u32 s19, 0
	s_cbranch_scc1 .Lgm_kloop
	s_waitcnt lgkmcnt(0)

.Lgm_fn_end:
	s_cmp_eq_u32 s30, 1
	s_cbranch_scc1 .Lgm_epi_kv
.Lgm_epi_none:
	global_load_dwordx4 v[216:219], v132, s[10:11]
	global_load_dwordx4 v[220:223], v133, s[10:11]
	global_load_dwordx4 v[224:227], v134, s[10:11]
	global_load_dwordx4 v[228:231], v135, s[10:11]
	global_load_dwordx4 v[144:147], v132, s[10:11] offset:128
	global_load_dwordx4 v[148:151], v133, s[10:11] offset:128
	global_load_dwordx4 v[152:155], v134, s[10:11] offset:128
	global_load_dwordx4 v[156:159], v135, s[10:11] offset:128
	global_load_dwordx4 v[184:187], v136, s[12:13] offset:0
	global_load_dwordx4 v[188:191], v136, s[12:13] offset:32
	global_load_dwordx4 v[192:195], v136, s[12:13] offset:64
	global_load_dwordx4 v[196:199], v136, s[12:13] offset:96
	s_add_u32 s10, s10, 256
	s_addc_u32 s11, s11, 0
	s_add_u32 s12, s12, 128
	s_addc_u32 s13, s13, 0
	s_mov_b32 s100, 0
	s_branch .Lgm_epi_done
.Lgm_epi_kv:
	s_add_i32 s0, s27, s96
	s_lshr_b32 s1, s0, 7
	s_and_b32 s32, s0, 127
	s_lshr_b32 s65, s31, 12
	s_and_b32 s68, s31, 0xfff
	s_cmp_lt_u32 s31, 0x8000
	s_cbranch_scc1 .Lgm_ri_0
	s_sub_i32 s65, s31, 0x8000
	s_lshr_b32 s65, s65, 8
	s_movk_i32 s68, 0x1000
.Lgm_ri_0:
	s_mul_i32 s65, s65, 6
	s_add_i32 s65, s65, s1
	s_mul_i32 s65, s65, 4352
	s_add_i32 s65, s65, s68
	s_cmp_lt_u32 s32, 64
	s_cbranch_scc1 .Lgm_kv_k
	s_lshl_b32 s65, s65, 7
	s_add_i32 s32, s32, -64
	s_lshl_b32 s32, s32, 1
	s_add_u32 s65, s65, s32
	s_add_u32 s65, s65, 0x1555d000
	s_movk_i32 s98, 128
	s_branch .Lgm_kv_j
.Lgm_kv_k:
	s_mul_i32 s65, s65, 192
	s_lshl_b32 s32, s32, 1
	s_add_u32 s65, s65, s32
	s_add_u32 s65, s65, 0x12f1d000
	s_movk_i32 s98, 192
.Lgm_kv_j:
	s_add_u32 s20, s50, s65
	s_addc_u32 s21, s51, 0
	s_lshl_b32 s99, s98, 5
	s_lshl_b32 s0, s31, 3
	s_add_u32 s0, s0, 0x1079000
	s_add_u32 s82, s50, s0
	s_addc_u32 s83, s51, 0
	v_and_b32_e32 v138, 31, v143
	v_bfe_u32 v139, v143, 5, 1
	v_mul_lo_u32 v137, s98, v138
	v_lshl_add_u32 v137, v139, 3, v137
	v_lshlrev_b32_e32 v181, 3, v138
	v_add_u32_e32 v181, 4, v181
	global_load_dword v200, v181, s[82:83] offset:0
	global_load_dword v201, v181, s[82:83] offset:256
	global_load_dword v202, v181, s[82:83] offset:512
	global_load_dword v203, v181, s[82:83] offset:768
	global_load_dword v204, v181, s[82:83] offset:1024
	global_load_dword v205, v181, s[82:83] offset:1280
	global_load_dword v206, v181, s[82:83] offset:1536
	global_load_dword v207, v181, s[82:83] offset:1792
	global_load_dwordx4 v[216:219], v132, s[10:11]
	global_load_dwordx4 v[220:223], v133, s[10:11]
	global_load_dwordx4 v[224:227], v134, s[10:11]
	global_load_dwordx4 v[228:231], v135, s[10:11]
	global_load_dwordx4 v[144:147], v132, s[10:11] offset:128
	global_load_dwordx4 v[148:151], v133, s[10:11] offset:128
	global_load_dwordx4 v[152:155], v134, s[10:11] offset:128
	global_load_dwordx4 v[156:159], v135, s[10:11] offset:128
	global_load_dwordx4 v[184:187], v136, s[12:13] offset:0
	global_load_dwordx4 v[188:191], v136, s[12:13] offset:32
	global_load_dwordx4 v[192:195], v136, s[12:13] offset:64
	global_load_dwordx4 v[196:199], v136, s[12:13] offset:96
	s_add_u32 s10, s10, 256
	s_addc_u32 s11, s11, 0
	s_add_u32 s12, s12, 128
	s_addc_u32 s13, s13, 0
	s_nop 7
	s_nop 3
	s_waitcnt vmcnt(19)
	v_mul_f32_e32 v0, v0, v200
	v_mul_f32_e32 v1, v1, v200
	v_mul_f32_e32 v2, v2, v200
	v_mul_f32_e32 v3, v3, v200
	v_cvt_pk_bf16_f32 v182, v0, v1
	v_cvt_pk_bf16_f32 v183, v2, v3
	global_store_dwordx2 v137, v[182:183], s[20:21] offset:0
	v_mul_f32_e32 v4, v4, v200
	v_mul_f32_e32 v5, v5, v200
	v_mul_f32_e32 v6, v6, v200
	v_mul_f32_e32 v7, v7, v200
	v_cvt_pk_bf16_f32 v182, v4, v5
	v_cvt_pk_bf16_f32 v183, v6, v7
	global_store_dwordx2 v137, v[182:183], s[20:21] offset:16
	v_mul_f32_e32 v8, v8, v200
	v_mul_f32_e32 v9, v9, v200
	v_mul_f32_e32 v10, v10, v200
	v_mul_f32_e32 v11, v11, v200
	v_cvt_pk_bf16_f32 v182, v8, v9
	v_cvt_pk_bf16_f32 v183, v10, v11
	global_store_dwordx2 v137, v[182:183], s[20:21] offset:32
	v_mul_f32_e32 v12, v12, v200
	v_mul_f32_e32 v13, v13, v200
	v_mul_f32_e32 v14, v14, v200
	v_mul_f32_e32 v15, v15, v200
	v_cvt_pk_bf16_f32 v182, v12, v13
	v_cvt_pk_bf16_f32 v183, v14, v15
	global_store_dwordx2 v137, v[182:183], s[20:21] offset:48
	s_add_u32 s20, s20, s99
	s_addc_u32 s21, s21, 0
	s_waitcnt vmcnt(22)
	v_mul_f32_e32 v16, v16, v201
	v_mul_f32_e32 v17, v17, v201
	v_mul_f32_e32 v18, v18, v201
	v_mul_f32_e32 v19, v19, v201
	v_cvt_pk_bf16_f32 v182, v16, v17
	v_cvt_pk_bf16_f32 v183, v18, v19
	global_store_dwordx2 v137, v[182:183], s[20:21] offset:0
	v_mul_f32_e32 v20, v20, v201
	v_mul_f32_e32 v21, v21, v201
	v_mul_f32_e32 v22, v22, v201
	v_mul_f32_e32 v23, v23, v201
	v_cvt_pk_bf16_f32 v182, v20, v21
	v_cvt_pk_bf16_f32 v183, v22, v23
	global_store_dwordx2 v137, v[182:183], s[20:21] offset:16
	v_mul_f32_e32 v24, v24, v201
	v_mul_f32_e32 v25, v25, v201
	v_mul_f32_e32 v26, v26, v201
	v_mul_f32_e32 v27, v27, v201
	v_cvt_pk_bf16_f32 v182, v24, v25
	v_cvt_pk_bf16_f32 v183, v26, v27
	global_store_dwordx2 v137, v[182:183], s[20:21] offset:32
	v_mul_f32_e32 v28, v28, v201
	v_mul_f32_e32 v29, v29, v201
	v_mul_f32_e32 v30, v30, v201
	v_mul_f32_e32 v31, v31, v201
	v_cvt_pk_bf16_f32 v182, v28, v29
	v_cvt_pk_bf16_f32 v183, v30, v31
	global_store_dwordx2 v137, v[182:183], s[20:21] offset:48
	s_add_u32 s20, s20, s99
	s_addc_u32 s21, s21, 0
	s_waitcnt vmcnt(25)
	v_mul_f32_e32 v32, v32, v202
	v_mul_f32_e32 v33, v33, v202
	v_mul_f32_e32 v34, v34, v202
	v_mul_f32_e32 v35, v35, v202
	v_cvt_pk_bf16_f32 v182, v32, v33
	v_cvt_pk_bf16_f32 v183, v34, v35
	global_store_dwordx2 v137, v[182:183], s[20:21] offset:0
	v_mul_f32_e32 v36, v36, v202
	v_mul_f32_e32 v37, v37, v202
	v_mul_f32_e32 v38, v38, v202
	v_mul_f32_e32 v39, v39, v202
	v_cvt_pk_bf16_f32 v182, v36, v37
	v_cvt_pk_bf16_f32 v183, v38, v39
	global_store_dwordx2 v137, v[182:183], s[20:21] offset:16
	v_mul_f32_e32 v40, v40, v202
	v_mul_f32_e32 v41, v41, v202
	v_mul_f32_e32 v42, v42, v202
	v_mul_f32_e32 v43, v43, v202
	v_cvt_pk_bf16_f32 v182, v40, v41
	v_cvt_pk_bf16_f32 v183, v42, v43
	global_store_dwordx2 v137, v[182:183], s[20:21] offset:32
	v_mul_f32_e32 v44, v44, v202
	v_mul_f32_e32 v45, v45, v202
	v_mul_f32_e32 v46, v46, v202
	v_mul_f32_e32 v47, v47, v202
	v_cvt_pk_bf16_f32 v182, v44, v45
	v_cvt_pk_bf16_f32 v183, v46, v47
	global_store_dwordx2 v137, v[182:183], s[20:21] offset:48
	s_add_u32 s20, s20, s99
	s_addc_u32 s21, s21, 0
	s_waitcnt vmcnt(28)
	v_mul_f32_e32 v48, v48, v203
	v_mul_f32_e32 v49, v49, v203
	v_mul_f32_e32 v50, v50, v203
	v_mul_f32_e32 v51, v51, v203
	v_cvt_pk_bf16_f32 v182, v48, v49
	v_cvt_pk_bf16_f32 v183, v50, v51
	global_store_dwordx2 v137, v[182:183], s[20:21] offset:0
	v_mul_f32_e32 v52, v52, v203
	v_mul_f32_e32 v53, v53, v203
	v_mul_f32_e32 v54, v54, v203
	v_mul_f32_e32 v55, v55, v203
	v_cvt_pk_bf16_f32 v182, v52, v53
	v_cvt_pk_bf16_f32 v183, v54, v55
	global_store_dwordx2 v137, v[182:183], s[20:21] offset:16
	v_mul_f32_e32 v56, v56, v203
	v_mul_f32_e32 v57, v57, v203
	v_mul_f32_e32 v58, v58, v203
	v_mul_f32_e32 v59, v59, v203
	v_cvt_pk_bf16_f32 v182, v56, v57
	v_cvt_pk_bf16_f32 v183, v58, v59
	global_store_dwordx2 v137, v[182:183], s[20:21] offset:32
	v_mul_f32_e32 v60, v60, v203
	v_mul_f32_e32 v61, v61, v203
	v_mul_f32_e32 v62, v62, v203
	v_mul_f32_e32 v63, v63, v203
	v_cvt_pk_bf16_f32 v182, v60, v61
	v_cvt_pk_bf16_f32 v183, v62, v63
	global_store_dwordx2 v137, v[182:183], s[20:21] offset:48
	s_add_u32 s20, s20, s99
	s_addc_u32 s21, s21, 0
	s_waitcnt vmcnt(31)
	v_mul_f32_e32 v64, v64, v204
	v_mul_f32_e32 v65, v65, v204
	v_mul_f32_e32 v66, v66, v204
	v_mul_f32_e32 v67, v67, v204
	v_cvt_pk_bf16_f32 v182, v64, v65
	v_cvt_pk_bf16_f32 v183, v66, v67
	global_store_dwordx2 v137, v[182:183], s[20:21] offset:0
	v_mul_f32_e32 v68, v68, v204
	v_mul_f32_e32 v69, v69, v204
	v_mul_f32_e32 v70, v70, v204
	v_mul_f32_e32 v71, v71, v204
	v_cvt_pk_bf16_f32 v182, v68, v69
	v_cvt_pk_bf16_f32 v183, v70, v71
	global_store_dwordx2 v137, v[182:183], s[20:21] offset:16
	v_mul_f32_e32 v72, v72, v204
	v_mul_f32_e32 v73, v73, v204
	v_mul_f32_e32 v74, v74, v204
	v_mul_f32_e32 v75, v75, v204
	v_cvt_pk_bf16_f32 v182, v72, v73
	v_cvt_pk_bf16_f32 v183, v74, v75
	global_store_dwordx2 v137, v[182:183], s[20:21] offset:32
	v_mul_f32_e32 v76, v76, v204
	v_mul_f32_e32 v77, v77, v204
	v_mul_f32_e32 v78, v78, v204
	v_mul_f32_e32 v79, v79, v204
	v_cvt_pk_bf16_f32 v182, v76, v77
	v_cvt_pk_bf16_f32 v183, v78, v79
	global_store_dwordx2 v137, v[182:183], s[20:21] offset:48
	s_add_u32 s20, s20, s99
	s_addc_u32 s21, s21, 0
	s_waitcnt vmcnt(34)
	v_mul_f32_e32 v80, v80, v205
	v_mul_f32_e32 v81, v81, v205
	v_mul_f32_e32 v82, v82, v205
	v_mul_f32_e32 v83, v83, v205
	v_cvt_pk_bf16_f32 v182, v80, v81
	v_cvt_pk_bf16_f32 v183, v82, v83
	global_store_dwordx2 v137, v[182:183], s[20:21] offset:0
	v_mul_f32_e32 v84, v84, v205
	v_mul_f32_e32 v85, v85, v205
	v_mul_f32_e32 v86, v86, v205
	v_mul_f32_e32 v87, v87, v205
	v_cvt_pk_bf16_f32 v182, v84, v85
	v_cvt_pk_bf16_f32 v183, v86, v87
	global_store_dwordx2 v137, v[182:183], s[20:21] offset:16
	v_mul_f32_e32 v88, v88, v205
	v_mul_f32_e32 v89, v89, v205
	v_mul_f32_e32 v90, v90, v205
	v_mul_f32_e32 v91, v91, v205
	v_cvt_pk_bf16_f32 v182, v88, v89
	v_cvt_pk_bf16_f32 v183, v90, v91
	global_store_dwordx2 v137, v[182:183], s[20:21] offset:32
	v_mul_f32_e32 v92, v92, v205
	v_mul_f32_e32 v93, v93, v205
	v_mul_f32_e32 v94, v94, v205
	v_mul_f32_e32 v95, v95, v205
	v_cvt_pk_bf16_f32 v182, v92, v93
	v_cvt_pk_bf16_f32 v183, v94, v95
	global_store_dwordx2 v137, v[182:183], s[20:21] offset:48
	s_add_u32 s20, s20, s99
	s_addc_u32 s21, s21, 0
	s_waitcnt vmcnt(37)
	v_mul_f32_e32 v96, v96, v206
	v_mul_f32_e32 v97, v97, v206
	v_mul_f32_e32 v98, v98, v206
	v_mul_f32_e32 v99, v99, v206
	v_cvt_pk_bf16_f32 v182, v96, v97
	v_cvt_pk_bf16_f32 v183, v98, v99
	global_store_dwordx2 v137, v[182:183], s[20:21] offset:0
	v_mul_f32_e32 v100, v100, v206
	v_mul_f32_e32 v101, v101, v206
	v_mul_f32_e32 v102, v102, v206
	v_mul_f32_e32 v103, v103, v206
	v_cvt_pk_bf16_f32 v182, v100, v101
	v_cvt_pk_bf16_f32 v183, v102, v103
	global_store_dwordx2 v137, v[182:183], s[20:21] offset:16
	v_mul_f32_e32 v104, v104, v206
	v_mul_f32_e32 v105, v105, v206
	v_mul_f32_e32 v106, v106, v206
	v_mul_f32_e32 v107, v107, v206
	v_cvt_pk_bf16_f32 v182, v104, v105
	v_cvt_pk_bf16_f32 v183, v106, v107
	global_store_dwordx2 v137, v[182:183], s[20:21] offset:32
	v_mul_f32_e32 v108, v108, v206
	v_mul_f32_e32 v109, v109, v206
	v_mul_f32_e32 v110, v110, v206
	v_mul_f32_e32 v111, v111, v206
	v_cvt_pk_bf16_f32 v182, v108, v109
	v_cvt_pk_bf16_f32 v183, v110, v111
	global_store_dwordx2 v137, v[182:183], s[20:21] offset:48
	s_add_u32 s20, s20, s99
	s_addc_u32 s21, s21, 0
	s_waitcnt vmcnt(40)
	v_mul_f32_e32 v112, v112, v207
	v_mul_f32_e32 v113, v113, v207
	v_mul_f32_e32 v114, v114, v207
	v_mul_f32_e32 v115, v115, v207
	v_cvt_pk_bf16_f32 v182, v112, v113
	v_cvt_pk_bf16_f32 v183, v114, v115
	global_store_dwordx2 v137, v[182:183], s[20:21] offset:0
	v_mul_f32_e32 v116, v116, v207
	v_mul_f32_e32 v117, v117, v207
	v_mul_f32_e32 v118, v118, v207
	v_mul_f32_e32 v119, v119, v207
	v_cvt_pk_bf16_f32 v182, v116, v117
	v_cvt_pk_bf16_f32 v183, v118, v119
	global_store_dwordx2 v137, v[182:183], s[20:21] offset:16
	v_mul_f32_e32 v120, v120, v207
	v_mul_f32_e32 v121, v121, v207
	v_mul_f32_e32 v122, v122, v207
	v_mul_f32_e32 v123, v123, v207
	v_cvt_pk_bf16_f32 v182, v120, v121
	v_cvt_pk_bf16_f32 v183, v122, v123
	global_store_dwordx2 v137, v[182:183], s[20:21] offset:32
	v_mul_f32_e32 v124, v124, v207
	v_mul_f32_e32 v125, v125, v207
	v_mul_f32_e32 v126, v126, v207
	v_mul_f32_e32 v127, v127, v207
	v_cvt_pk_bf16_f32 v182, v124, v125
	v_cvt_pk_bf16_f32 v183, v126, v127
	global_store_dwordx2 v137, v[182:183], s[20:21] offset:48
	s_movk_i32 s100, 32
	s_branch .Lgm_epi_done
.Lgm_epi_done:
	s_cmp_lg_u32 s101, 0
	s_cbranch_scc1 .Lgm_tile
.Lgm_done:
	s_waitcnt vmcnt(0)
	s_movk_i32 s64, 0x240
	v_mov_b32_e32 v0, v143
	s_mov_b64 exec, -1
	s_and_b64 vcc, exec, s[72:73]
	s_cbranch_vccz .LBB0_419
	v_readlane_b32 s4, v255, 23
	s_mov_b32 s1, 0
	s_mov_b32 s0, 0
	v_readlane_b32 s16, v253, 0
	v_readlane_b32 s5, v255, 24
	s_mov_b32 s17, s4
	s_branch .LBB0_420
